# nsa_main attention tile: P*V accumulated in place in the loop-carried O registers, 64 copy-back v_mov per tile removed (on top of v8)
# speedup vs baseline: 1.0176x; 1.0038x over previous
; #define MFMA32(a, b, c) __builtin_amdgcn_mfma_f32_32x32x16_bf16((a), (b), (c), 0, 0, 0)
; template <int MODE, int KIND> __device__ __forceinline__ void attn_tile(const LAS unsigned char* fq, const LAS unsigned char* tb, float msk, int dlim, const bf16x8 (&qf)[8], f32x16 (&O)[4], float& lsum) {
;     ...
;     u32x4 fa[4], fb[4]; f32x16 S0, S1; bf16x8 pb0[2], pb1[2];
;     ATT_SINIT(S0, 0);
; #pragma unroll
;     for (int s = 0; s < 4; ++s) fa[s] = ATT_KF(0, s);
;     ATT_SB();
; #pragma unroll
;     for (int s = 0; s < 4; ++s) fb[s] = ATT_KF(0, 4 + s);
; #pragma unroll
;     for (int s = 0; s < 4; ++s) S0 = MFMA32(ATT_BF(fa[s]), qf[s], S0);
;     ATT_SB();
; #pragma unroll
;     for (int s = 0; s < 4; ++s) fa[s] = ATT_KF(1, s);
;     ATT_SINIT(S1, 1);
; #pragma unroll
;     for (int s = 0; s < 4; ++s) S0 = MFMA32(ATT_BF(fb[s]), qf[4 + s], S0);
;     ATT_SB();
; #pragma unroll
;     for (int s = 0; s < 4; ++s) fb[s] = ATT_KF(1, 4 + s);
; #pragma unroll
;     for (int s = 0; s < 4; ++s) S1 = MFMA32(ATT_BF(fa[s]), qf[s], S1);
;     ATT_SB();
;     fa[0] = ATT_VF(0, 0); fa[1] = ATT_VF(0, 1); fa[2] = ATT_VF(1, 0); fa[3] = ATT_VF(1, 1);
; #pragma unroll
;     for (int s = 0; s < 4; ++s) S1 = MFMA32(ATT_BF(fb[s]), qf[4 + s], S1);
;     ATT_EXP(S0, 0, pb0);
;     ATT_SB();
;     fb[0] = ATT_VF(2, 0); fb[1] = ATT_VF(2, 1); fb[2] = ATT_VF(3, 0); fb[3] = ATT_VF(3, 1);
;     O[0] = MFMA32(ATT_BF(fa[0]), pb0[0], O[0]); O[0] = MFMA32(ATT_BF(fa[1]), pb0[1], O[0]); O[1] = MFMA32(ATT_BF(fa[2]), pb0[0], O[1]); O[1] = MFMA32(ATT_BF(fa[3]), pb0[1], O[1]);
;     ATT_EXP(S1, 1, pb1);
;     ATT_SB();
;     fa[0] = ATT_VF(0, 2); fa[1] = ATT_VF(0, 3); fa[2] = ATT_VF(1, 2); fa[3] = ATT_VF(1, 3);
;     O[2] = MFMA32(ATT_BF(fb[0]), pb0[0], O[2]); O[2] = MFMA32(ATT_BF(fb[1]), pb0[1], O[2]); O[3] = MFMA32(ATT_BF(fb[2]), pb0[0], O[3]); O[3] = MFMA32(ATT_BF(fb[3]), pb0[1], O[3]);
;     ATT_SB();
;     fb[0] = ATT_VF(2, 2); fb[1] = ATT_VF(2, 3); fb[2] = ATT_VF(3, 2); fb[3] = ATT_VF(3, 3);
;     O[0] = MFMA32(ATT_BF(fa[0]), pb1[0], O[0]); O[0] = MFMA32(ATT_BF(fa[1]), pb1[1], O[0]); O[1] = MFMA32(ATT_BF(fa[2]), pb1[0], O[1]); O[1] = MFMA32(ATT_BF(fa[3]), pb1[1], O[1]);
;     ATT_SB();
;     O[2] = MFMA32(ATT_BF(fb[0]), pb1[0], O[2]); O[2] = MFMA32(ATT_BF(fb[1]), pb1[1], O[2]); O[3] = MFMA32(ATT_BF(fb[2]), pb1[0], O[3]); O[3] = MFMA32(ATT_BF(fb[3]), pb1[1], O[3]);
;     ATT_SB();
.LBB0_1856:
	s_cmp_le_i32 s34, s62
	s_cselect_b64 s[12:13], -1, 0
	s_add_i32 s15, s34, 63
	s_cmp_ge_i32 s15, s19
	s_cselect_b64 s[26:27], -1, 0
	s_and_b64 s[12:13], s[12:13], s[26:27]
	s_andn2_b64 vcc, exec, s[12:13]
	s_cbranch_vccnz .LBB0_1866
	s_add_i32 s12, s35, 0xffffffa2
	v_lshl_add_u32 v2, s14, 15, v1
	s_cmpk_lt_i32 s12, 0x80
	s_mov_b64 s[12:13], -1
	s_cbranch_scc0 .LBB0_1859
	ds_read_b128 v[68:71], v183
	ds_read_b128 v[72:75], v183 offset:32
	ds_read_b128 v[76:79], v183 offset:64
	ds_read_b128 v[80:83], v183 offset:96
	ds_read_b128 v[84:87], v2
	ds_read_b128 v[88:91], v2 offset:1024
	ds_read_b128 v[92:95], v2 offset:2048
	ds_read_b128 v[96:99], v2 offset:3072
	ds_read_b128 v[108:111], v2 offset:4096
	ds_read_b128 v[112:115], v2 offset:5120
	ds_read_b128 v[116:119], v2 offset:6144
	ds_read_b128 v[120:123], v2 offset:7168
	s_waitcnt lgkmcnt(0)
	v_mfma_f32_32x32x16_bf16 v[68:83], v[84:87], v[132:135], v[68:83]
	ds_read_b128 v[124:127], v2 offset:8192
	ds_read_b128 v[128:131], v2 offset:9216
	ds_read_b128 v[164:167], v2 offset:10240
	ds_read_b128 v[168:171], v2 offset:11264
	v_mfma_f32_32x32x16_bf16 v[68:83], v[88:91], v[136:139], v[68:83]
	v_mfma_f32_32x32x16_bf16 v[68:83], v[92:95], v[140:143], v[68:83]
	v_mfma_f32_32x32x16_bf16 v[68:83], v[96:99], v[144:147], v[68:83]
	ds_read_b128 v[92:95], v183 offset:128
	ds_read_b128 v[96:99], v183 offset:160
	ds_read_b128 v[100:103], v183 offset:192
	ds_read_b128 v[104:107], v183 offset:224
	s_waitcnt lgkmcnt(0)
	v_mfma_f32_32x32x16_bf16 v[92:107], v[124:127], v[132:135], v[92:107]
	v_mfma_f32_32x32x16_bf16 v[92:107], v[128:131], v[136:139], v[92:107]
	v_mfma_f32_32x32x16_bf16 v[68:83], v[108:111], v[148:151], v[68:83]
	v_mfma_f32_32x32x16_bf16 v[92:107], v[164:167], v[140:143], v[92:107]
	v_mfma_f32_32x32x16_bf16 v[68:83], v[112:115], v[152:155], v[68:83]
	ds_read_b128 v[84:87], v2 offset:12288
	ds_read_b128 v[88:91], v2 offset:13312
	ds_read_b128 v[108:111], v2 offset:14336
	ds_read_b128 v[112:115], v2 offset:15360
	v_mfma_f32_32x32x16_bf16 v[92:107], v[168:171], v[144:147], v[92:107]
	v_mfma_f32_32x32x16_bf16 v[68:83], v[116:119], v[156:159], v[68:83]
	s_waitcnt lgkmcnt(0)
	v_mfma_f32_32x32x16_bf16 v[92:107], v[84:87], v[148:151], v[92:107]
	ds_read_b128 v[116:119], v2 offset:16384
	ds_read_b128 v[124:127], v2 offset:17408
	ds_read_b128 v[128:131], v2 offset:20480
	ds_read_b128 v[164:167], v2 offset:21504
	v_mfma_f32_32x32x16_bf16 v[68:83], v[120:123], v[160:163], v[68:83]
	v_mfma_f32_32x32x16_bf16 v[92:107], v[88:91], v[152:155], v[92:107]
	s_nop 10
	v_exp_f32_e32 v68, v68
	v_exp_f32_e32 v69, v69
	v_exp_f32_e32 v70, v70
	v_exp_f32_e32 v71, v71
	v_exp_f32_e32 v72, v72
	v_add_f32_e32 v120, v197, v68
	v_exp_f32_e32 v73, v73
	v_mfma_f32_32x32x16_bf16 v[92:107], v[108:111], v[156:159], v[92:107]
	v_add_f32_e32 v120, v69, v120
	v_exp_f32_e32 v74, v74
	v_add_f32_e32 v120, v70, v120
	v_add_f32_e32 v120, v71, v120
	v_exp_f32_e32 v75, v75
	v_add_f32_e32 v120, v72, v120
	v_exp_f32_e32 v76, v76
	v_add_f32_e32 v120, v73, v120
	v_exp_f32_e32 v77, v77
	v_add_f32_e32 v120, v74, v120
	v_exp_f32_e32 v78, v78
	v_add_f32_e32 v120, v75, v120
	v_exp_f32_e32 v79, v79
	v_add_f32_e32 v84, v76, v120
	v_exp_f32_e32 v80, v80
	v_mfma_f32_32x32x16_bf16 v[92:107], v[112:115], v[160:163], v[92:107]
	v_add_f32_e32 v84, v77, v84
	v_exp_f32_e32 v81, v81
	v_add_f32_e32 v84, v78, v84
	v_exp_f32_e32 v82, v82
	v_add_f32_e32 v84, v79, v84
	v_exp_f32_e32 v83, v83
	v_add_f32_e32 v84, v80, v84
	v_add_f32_e32 v84, v81, v84
	v_add_f32_e32 v84, v82, v84
	v_add_f32_e32 v84, v83, v84
	v_cvt_pk_bf16_f32 v168, v68, v69
	v_cvt_pk_bf16_f32 v169, v70, v71
	v_cvt_pk_bf16_f32 v170, v72, v73
	v_cvt_pk_bf16_f32 v171, v74, v75
	v_cvt_pk_bf16_f32 v172, v76, v77
	v_cvt_pk_bf16_f32 v173, v78, v79
	v_cvt_pk_bf16_f32 v174, v80, v81
	v_cvt_pk_bf16_f32 v175, v82, v83
	v_exp_f32_e32 v108, v92
	v_exp_f32_e32 v109, v93
	v_exp_f32_e32 v110, v94
	v_exp_f32_e32 v111, v95
	v_add_f32_e32 v84, v108, v84
	v_exp_f32_e32 v112, v96
	v_add_f32_e32 v84, v109, v84
	v_exp_f32_e32 v113, v97
	v_add_f32_e32 v84, v110, v84
	v_exp_f32_e32 v114, v98
	v_add_f32_e32 v84, v111, v84
	v_add_f32_e32 v84, v112, v84
	v_add_f32_e32 v84, v113, v84
	s_waitcnt lgkmcnt(0)
	v_mfma_f32_32x32x16_bf16 v[52:67], v[116:119], v[168:171], v[52:67]
	v_exp_f32_e32 v115, v99
	v_add_f32_e32 v116, v114, v84
	v_exp_f32_e32 v100, v100
	v_exp_f32_e32 v101, v101
	v_exp_f32_e32 v102, v102
	v_add_f32_e32 v116, v115, v116
	v_exp_f32_e32 v103, v103
	v_mfma_f32_32x32x16_bf16 v[36:51], v[128:131], v[168:171], v[36:51]
	v_add_f32_e32 v116, v100, v116
	v_exp_f32_e32 v104, v104
	v_add_f32_e32 v116, v101, v116
	v_exp_f32_e32 v105, v105
	v_add_f32_e32 v116, v102, v116
	v_exp_f32_e32 v106, v106
	ds_read_b128 v[120:123], v2 offset:24576
	ds_read_b128 v[176:179], v2 offset:25600
	v_mfma_f32_32x32x16_bf16 v[52:67], v[124:127], v[172:175], v[52:67]
	ds_read_b128 v[198:201], v2 offset:28672
	ds_read_b128 v[202:205], v2 offset:29696
	v_add_f32_e32 v116, v103, v116
	v_exp_f32_e32 v107, v107
	v_add_f32_e32 v116, v104, v116
	v_add_f32_e32 v116, v105, v116
	v_add_f32_e32 v116, v106, v116
	v_add_f32_e32 v184, v107, v116
	v_mfma_f32_32x32x16_bf16 v[36:51], v[164:167], v[172:175], v[36:51]
	v_cvt_pk_bf16_f32 v164, v108, v109
	v_cvt_pk_bf16_f32 v165, v110, v111
	v_cvt_pk_bf16_f32 v166, v112, v113
	v_cvt_pk_bf16_f32 v167, v114, v115
	v_cvt_pk_bf16_f32 v206, v100, v101
	v_cvt_pk_bf16_f32 v207, v102, v103
	v_cvt_pk_bf16_f32 v208, v104, v105
	v_cvt_pk_bf16_f32 v209, v106, v107
	s_waitcnt lgkmcnt(0)
	v_mfma_f32_32x32x16_bf16 v[20:35], v[120:123], v[168:171], v[20:35]
	v_mfma_f32_32x32x16_bf16 v[4:19], v[198:201], v[168:171], v[4:19]
	v_mfma_f32_32x32x16_bf16 v[20:35], v[176:179], v[172:175], v[20:35]
	ds_read_b128 v[168:171], v2 offset:18432
	ds_read_b128 v[176:179], v2 offset:19456
	ds_read_b128 v[198:201], v2 offset:22528
	ds_read_b128 v[210:213], v2 offset:23552
	v_mfma_f32_32x32x16_bf16 v[4:19], v[202:205], v[172:175], v[4:19]
	s_waitcnt lgkmcnt(0)
	v_mfma_f32_32x32x16_bf16 v[52:67], v[168:171], v[164:167], v[52:67]
	v_mfma_f32_32x32x16_bf16 v[36:51], v[198:201], v[164:167], v[36:51]
	v_mfma_f32_32x32x16_bf16 v[52:67], v[176:179], v[206:209], v[52:67]
	ds_read_b128 v[168:171], v2 offset:26624
	ds_read_b128 v[172:175], v2 offset:27648
	ds_read_b128 v[176:179], v2 offset:30720
	ds_read_b128 v[198:201], v2 offset:31744
	v_mfma_f32_32x32x16_bf16 v[36:51], v[210:213], v[206:209], v[36:51]
	s_waitcnt lgkmcnt(0)
	v_mfma_f32_32x32x16_bf16 v[20:35], v[168:171], v[164:167], v[20:35]
	v_mfma_f32_32x32x16_bf16 v[4:19], v[176:179], v[164:167], v[4:19]
	v_mfma_f32_32x32x16_bf16 v[20:35], v[172:175], v[206:209], v[20:35]
	v_mfma_f32_32x32x16_bf16 v[4:19], v[198:201], v[206:209], v[4:19]
	s_mov_b64 s[12:13], 0
; #define MFMA32(a, b, c) __builtin_amdgcn_mfma_f32_32x32x16_bf16((a), (b), (c), 0, 0, 0)
; #define ATT_SB() __builtin_amdgcn_sched_barrier(0)
; #define ATT_SINIT(S_, half_) do { if (KIND == 1) { _Pragma("unroll") for (int gq = 0; gq < 4; ++gq) { const f32x4 bv = *(const LAS f32x4*)(tb + 4 * (8 * gq + 32 * (half_))); \
;             S_[4 * gq] = bv[0]; S_[4 * gq + 1] = bv[1]; S_[4 * gq + 2] = bv[2]; S_[4 * gq + 3] = bv[3]; } } else { _Pragma("unroll") for (int i = 0; i < 16; ++i) S_[i] = 0.f; } } while (0)
; template <int MODE, int KIND> __device__ __forceinline__ void attn_tile(const LAS unsigned char* fq, const LAS unsigned char* tb, float msk, int dlim, const bf16x8 (&qf)[8], f32x16 (&O)[4], float& lsum) {
;     ...
;     u32x4 fa[4], fb[4]; f32x16 S0, S1; bf16x8 pb0[2], pb1[2];
;     ATT_SINIT(S0, 0);
; #pragma unroll
;     for (int s = 0; s < 4; ++s) fa[s] = ATT_KF(0, s);
;     ATT_SB();
; #pragma unroll
;     for (int s = 0; s < 4; ++s) fb[s] = ATT_KF(0, 4 + s);
; #pragma unroll
;     for (int s = 0; s < 4; ++s) S0 = MFMA32(ATT_BF(fa[s]), qf[s], S0);
;     ATT_SB();
; #pragma unroll
;     for (int s = 0; s < 4; ++s) fa[s] = ATT_KF(1, s);
;     ATT_SINIT(S1, 1);
; #pragma unroll
;     for (int s = 0; s < 4; ++s) S0 = MFMA32(ATT_BF(fb[s]), qf[4 + s], S0);
;     ATT_SB();
; #pragma unroll
;     for (int s = 0; s < 4; ++s) fb[s] = ATT_KF(1, 4 + s);
; #pragma unroll
;     for (int s = 0; s < 4; ++s) S1 = MFMA32(ATT_BF(fa[s]), qf[s], S1);
;     ATT_SB();
;     fa[0] = ATT_VF(0, 0); fa[1] = ATT_VF(0, 1); fa[2] = ATT_VF(1, 0); fa[3] = ATT_VF(1, 1);
; #pragma unroll
;     for (int s = 0; s < 4; ++s) S1 = MFMA32(ATT_BF(fb[s]), qf[4 + s], S1);
;     ATT_EXP(S0, 0, pb0);
;     ATT_SB();
;     fb[0] = ATT_VF(2, 0); fb[1] = ATT_VF(2, 1); fb[2] = ATT_VF(3, 0); fb[3] = ATT_VF(3, 1);
;     O[0] = MFMA32(ATT_BF(fa[0]), pb0[0], O[0]); O[0] = MFMA32(ATT_BF(fa[1]), pb0[1], O[0]); O[1] = MFMA32(ATT_BF(fa[2]), pb0[0], O[1]); O[1] = MFMA32(ATT_BF(fa[3]), pb0[1], O[1]);
;     ATT_EXP(S1, 1, pb1);
.LBB0_1859:
	s_andn2_b64 vcc, exec, s[12:13]
	s_cbranch_vccnz .LBB0_1864
	s_waitcnt lgkmcnt(0)
	ds_read_b128 v[176:179], v2
	ds_read_b128 v[172:175], v2 offset:1024
	ds_read_b128 v[168:171], v2 offset:2048
	ds_read_b128 v[164:167], v2 offset:3072
	s_cmpk_gt_i32 s35, 0x1ff
	s_mov_b64 s[12:13], -1
	s_cbranch_scc0 .LBB0_1862
	v_add_u32_e32 v68, s35, v181
	v_subrev_u32_e32 v184, 31, v68
	ds_read_b128 v[84:87], v2 offset:4096
	ds_read_b128 v[88:91], v2 offset:5120
	ds_read_b128 v[92:95], v2 offset:6144
	ds_read_b128 v[96:99], v2 offset:7168
	s_waitcnt lgkmcnt(0)
	v_mfma_f32_32x32x16_bf16 v[68:83], v[176:179], v[132:135], 0
	v_mfma_f32_32x32x16_bf16 v[68:83], v[172:175], v[136:139], v[68:83]
	v_mfma_f32_32x32x16_bf16 v[68:83], v[168:171], v[140:143], v[68:83]
	v_mfma_f32_32x32x16_bf16 v[68:83], v[164:167], v[144:147], v[68:83]
	v_mfma_f32_32x32x16_bf16 v[68:83], v[84:87], v[148:151], v[68:83]
	v_mfma_f32_32x32x16_bf16 v[68:83], v[88:91], v[152:155], v[68:83]
	v_mfma_f32_32x32x16_bf16 v[68:83], v[92:95], v[156:159], v[68:83]
	ds_read_b128 v[84:87], v2 offset:8192
	ds_read_b128 v[88:91], v2 offset:9216
	ds_read_b128 v[92:95], v2 offset:10240
	ds_read_b128 v[112:115], v2 offset:11264
	v_mfma_f32_32x32x16_bf16 v[68:83], v[96:99], v[160:163], v[68:83]
	s_waitcnt lgkmcnt(0)
	v_mfma_f32_32x32x16_bf16 v[96:111], v[84:87], v[132:135], 0
	v_mfma_f32_32x32x16_bf16 v[96:111], v[88:91], v[136:139], v[96:111]
	v_mfma_f32_32x32x16_bf16 v[96:111], v[92:95], v[140:143], v[96:111]
	ds_read_b128 v[84:87], v2 offset:12288
	ds_read_b128 v[88:91], v2 offset:13312
	ds_read_b128 v[92:95], v2 offset:14336
	ds_read_b128 v[116:119], v2 offset:15360
	v_mfma_f32_32x32x16_bf16 v[96:111], v[112:115], v[144:147], v[96:111]
	s_waitcnt lgkmcnt(0)
	v_mfma_f32_32x32x16_bf16 v[96:111], v[84:87], v[148:151], v[96:111]
	s_nop 0
	v_exp_f32_e32 v68, v68
	v_exp_f32_e32 v69, v69
	v_exp_f32_e32 v70, v70
	v_cmp_gt_i32_e32 vcc, s30, v184
	s_movk_i32 s12, 0x201
	v_exp_f32_e32 v71, v71
	v_cndmask_b32_e32 v68, 0, v68, vcc
	v_mfma_f32_32x32x16_bf16 v[96:111], v[88:91], v[152:155], v[96:111]
	v_cmp_gt_i32_e32 vcc, s12, v184
	s_movk_i32 s12, 0x202
	v_exp_f32_e32 v72, v72
	v_add_f32_e32 v185, v197, v68
	v_cndmask_b32_e32 v69, 0, v69, vcc
	v_cmp_gt_i32_e32 vcc, s12, v184
	s_movk_i32 s12, 0x203
	v_exp_f32_e32 v73, v73
	v_mfma_f32_32x32x16_bf16 v[96:111], v[92:95], v[156:159], v[96:111]
	v_add_f32_e32 v185, v69, v185
	v_cndmask_b32_e32 v70, 0, v70, vcc
	v_cmp_gt_i32_e32 vcc, s12, v184
	s_movk_i32 s12, 0x208
	v_exp_f32_e32 v74, v74
	v_add_f32_e32 v185, v70, v185
	v_cndmask_b32_e32 v71, 0, v71, vcc
	v_cmp_gt_i32_e32 vcc, s12, v184
	s_movk_i32 s12, 0x209
	v_exp_f32_e32 v75, v75
	v_add_f32_e32 v185, v71, v185
	v_cndmask_b32_e32 v72, 0, v72, vcc
	v_cmp_gt_i32_e32 vcc, s12, v184
	s_movk_i32 s12, 0x20a
	v_exp_f32_e32 v76, v76
	v_add_f32_e32 v185, v72, v185
	v_cndmask_b32_e32 v73, 0, v73, vcc
	v_cmp_gt_i32_e32 vcc, s12, v184
	s_movk_i32 s12, 0x20b
	v_exp_f32_e32 v77, v77
	v_add_f32_e32 v185, v73, v185
	v_cndmask_b32_e32 v74, 0, v74, vcc
	v_cmp_gt_i32_e32 vcc, s12, v184
	v_exp_f32_e32 v78, v78
	v_add_f32_e32 v185, v74, v185
	v_cndmask_b32_e32 v75, 0, v75, vcc
	v_cmp_gt_i32_e32 vcc, s81, v184
	s_movk_i32 s12, 0x211
	v_exp_f32_e32 v79, v79
	v_add_f32_e32 v185, v75, v185
	v_cndmask_b32_e32 v76, 0, v76, vcc
	v_cmp_gt_i32_e32 vcc, s12, v184
	s_movk_i32 s12, 0x212
	v_exp_f32_e32 v80, v80
	v_add_f32_e32 v185, v76, v185
	v_cndmask_b32_e32 v77, 0, v77, vcc
	v_cmp_gt_i32_e32 vcc, s12, v184
	s_movk_i32 s12, 0x213
	v_exp_f32_e32 v81, v81
	v_mfma_f32_32x32x16_bf16 v[96:111], v[116:119], v[160:163], v[96:111]
	v_add_f32_e32 v185, v77, v185
	v_cndmask_b32_e32 v78, 0, v78, vcc
	v_cmp_gt_i32_e32 vcc, s12, v184
	s_movk_i32 s12, 0x218
	v_exp_f32_e32 v82, v82
	v_add_f32_e32 v185, v78, v185
	v_cndmask_b32_e32 v79, 0, v79, vcc
	v_cmp_gt_i32_e32 vcc, s12, v184
	s_movk_i32 s12, 0x219
	v_exp_f32_e32 v83, v83
	ds_read_b128 v[112:115], v2 offset:16384
	ds_read_b128 v[120:123], v2 offset:17408
	ds_read_b128 v[124:127], v2 offset:20480
	ds_read_b128 v[128:131], v2 offset:21504
	v_add_f32_e32 v185, v79, v185
	v_cndmask_b32_e32 v80, 0, v80, vcc
	v_cmp_gt_i32_e32 vcc, s12, v184
	s_movk_i32 s12, 0x21a
	v_add_f32_e32 v84, v80, v185
	v_cndmask_b32_e32 v81, 0, v81, vcc
	v_cmp_gt_i32_e32 vcc, s12, v184
	s_movk_i32 s12, 0x21b
	v_add_f32_e32 v84, v81, v84
	v_cndmask_b32_e32 v82, 0, v82, vcc
	v_cmp_gt_i32_e32 vcc, s12, v184
	v_add_f32_e32 v84, v82, v84
	v_cvt_pk_bf16_f32 v198, v68, v69
	v_cndmask_b32_e32 v83, 0, v83, vcc
	v_add_f32_e32 v84, v83, v84
	v_cvt_pk_bf16_f32 v199, v70, v71
	v_cvt_pk_bf16_f32 v200, v72, v73
	v_cvt_pk_bf16_f32 v201, v74, v75
	v_cvt_pk_bf16_f32 v202, v76, v77
	v_cvt_pk_bf16_f32 v203, v78, v79
	v_cvt_pk_bf16_f32 v204, v80, v81
	v_cvt_pk_bf16_f32 v205, v82, v83
	v_exp_f32_e32 v85, v96
	v_exp_f32_e32 v86, v97
	s_waitcnt lgkmcnt(0)
; #define MFMA32(a, b, c) __builtin_amdgcn_mfma_f32_32x32x16_bf16((a), (b), (c), 0, 0, 0)
; #define ATT_SB() __builtin_amdgcn_sched_barrier(0)
; template <int MODE, int KIND> __device__ __forceinline__ void attn_tile(const LAS unsigned char* fq, const LAS unsigned char* tb, float msk, int dlim, const bf16x8 (&qf)[8], f32x16 (&O)[4], float& lsum) {
;     ...
;     ATT_EXP(S0, 0, pb0);
;     ATT_SB();
;     fb[0] = ATT_VF(2, 0); fb[1] = ATT_VF(2, 1); fb[2] = ATT_VF(3, 0); fb[3] = ATT_VF(3, 1);
;     O[0] = MFMA32(ATT_BF(fa[0]), pb0[0], O[0]); O[0] = MFMA32(ATT_BF(fa[1]), pb0[1], O[0]); O[1] = MFMA32(ATT_BF(fa[2]), pb0[0], O[1]); O[1] = MFMA32(ATT_BF(fa[3]), pb0[1], O[1]);
;     ATT_EXP(S1, 1, pb1);
;     ATT_SB();
;     fa[0] = ATT_VF(0, 2); fa[1] = ATT_VF(0, 3); fa[2] = ATT_VF(1, 2); fa[3] = ATT_VF(1, 3);
;     O[2] = MFMA32(ATT_BF(fb[0]), pb0[0], O[2]); O[2] = MFMA32(ATT_BF(fb[1]), pb0[1], O[2]); O[3] = MFMA32(ATT_BF(fb[2]), pb0[0], O[3]); O[3] = MFMA32(ATT_BF(fb[3]), pb0[1], O[3]);
;     ATT_SB();
;     fb[0] = ATT_VF(2, 2); fb[1] = ATT_VF(2, 3); fb[2] = ATT_VF(3, 2); fb[3] = ATT_VF(3, 3);
;     O[0] = MFMA32(ATT_BF(fa[0]), pb1[0], O[0]); O[0] = MFMA32(ATT_BF(fa[1]), pb1[1], O[0]); O[1] = MFMA32(ATT_BF(fa[2]), pb1[0], O[1]); O[1] = MFMA32(ATT_BF(fa[3]), pb1[1], O[1]);
;     ATT_SB();
;     O[2] = MFMA32(ATT_BF(fb[0]), pb1[0], O[2]); O[2] = MFMA32(ATT_BF(fb[1]), pb1[1], O[2]); O[3] = MFMA32(ATT_BF(fb[2]), pb1[0], O[3]); O[3] = MFMA32(ATT_BF(fb[3]), pb1[1], O[3]);
;     ATT_SB();
	v_mfma_f32_32x32x16_bf16 v[52:67], v[112:115], v[198:201], v[52:67]
	s_movk_i32 s12, 0x220
	v_cmp_gt_i32_e32 vcc, s12, v184
	s_movk_i32 s12, 0x221
	v_exp_f32_e32 v100, v100
	v_cndmask_b32_e32 v112, 0, v85, vcc
	v_cmp_gt_i32_e32 vcc, s12, v184
	v_exp_f32_e32 v85, v98
	s_movk_i32 s12, 0x222
	v_cndmask_b32_e32 v113, 0, v86, vcc
	v_exp_f32_e32 v86, v99
	v_add_f32_e32 v84, v84, v112
	v_cmp_gt_i32_e32 vcc, s12, v184
	s_movk_i32 s12, 0x223
	v_add_f32_e32 v84, v113, v84
	v_cndmask_b32_e32 v114, 0, v85, vcc
	v_cmp_gt_i32_e32 vcc, s12, v184
	v_mfma_f32_32x32x16_bf16 v[52:67], v[120:123], v[202:205], v[52:67]
	v_add_f32_e32 v115, v114, v84
	v_cndmask_b32_e32 v120, 0, v86, vcc
	v_exp_f32_e32 v101, v101
	s_movk_i32 s12, 0x228
	v_exp_f32_e32 v102, v102
	v_cmp_gt_i32_e32 vcc, s12, v184
	s_movk_i32 s12, 0x229
	v_mfma_f32_32x32x16_bf16 v[36:51], v[124:127], v[198:201], v[36:51]
	v_exp_f32_e32 v103, v103
	v_add_f32_e32 v115, v120, v115
	v_cndmask_b32_e32 v100, 0, v100, vcc
	v_cmp_gt_i32_e32 vcc, s12, v184
	s_movk_i32 s12, 0x22a
	v_exp_f32_e32 v104, v104
	v_add_f32_e32 v115, v100, v115
	v_cndmask_b32_e32 v101, 0, v101, vcc
	v_cmp_gt_i32_e32 vcc, s12, v184
	s_movk_i32 s12, 0x22b
	v_exp_f32_e32 v105, v105
	v_add_f32_e32 v115, v101, v115
	v_cndmask_b32_e32 v102, 0, v102, vcc
	v_cmp_gt_i32_e32 vcc, s12, v184
	s_movk_i32 s12, 0x230
	v_exp_f32_e32 v106, v106
	v_add_f32_e32 v115, v102, v115
	v_cndmask_b32_e32 v103, 0, v103, vcc
	v_cmp_gt_i32_e32 vcc, s12, v184
	s_movk_i32 s12, 0x231
	v_exp_f32_e32 v107, v107
	v_add_f32_e32 v115, v103, v115
	v_cndmask_b32_e32 v104, 0, v104, vcc
	v_cmp_gt_i32_e32 vcc, s12, v184
	s_movk_i32 s12, 0x232
	v_exp_f32_e32 v108, v108
	v_mfma_f32_32x32x16_bf16 v[36:51], v[128:131], v[202:205], v[36:51]
	v_add_f32_e32 v115, v104, v115
	v_cndmask_b32_e32 v105, 0, v105, vcc
	v_cmp_gt_i32_e32 vcc, s12, v184
	s_movk_i32 s12, 0x233
	v_exp_f32_e32 v109, v109
	ds_read_b128 v[116:119], v2 offset:24576
	ds_read_b128 v[206:209], v2 offset:25600
	ds_read_b128 v[210:213], v2 offset:28672
	ds_read_b128 v[214:217], v2 offset:29696
	v_add_f32_e32 v115, v105, v115
	v_cndmask_b32_e32 v106, 0, v106, vcc
	v_cmp_gt_i32_e32 vcc, s12, v184
	s_movk_i32 s12, 0x238
	v_exp_f32_e32 v110, v110
	v_add_f32_e32 v115, v106, v115
	v_cndmask_b32_e32 v107, 0, v107, vcc
	v_cmp_gt_i32_e32 vcc, s12, v184
	s_movk_i32 s12, 0x239
	v_exp_f32_e32 v111, v111
	v_add_f32_e32 v115, v107, v115
	v_cndmask_b32_e32 v108, 0, v108, vcc
	v_cmp_gt_i32_e32 vcc, s12, v184
	s_movk_i32 s12, 0x23a
	v_add_f32_e32 v115, v108, v115
	v_cndmask_b32_e32 v109, 0, v109, vcc
	v_cmp_gt_i32_e32 vcc, s12, v184
	s_movk_i32 s12, 0x23b
	v_add_f32_e32 v115, v109, v115
	v_cndmask_b32_e32 v110, 0, v110, vcc
	v_cmp_gt_i32_e32 vcc, s12, v184
	v_add_f32_e32 v115, v110, v115
	v_cvt_pk_bf16_f32 v218, v112, v113
	v_cndmask_b32_e32 v111, 0, v111, vcc
	v_add_f32_e32 v184, v111, v115
	v_cvt_pk_bf16_f32 v219, v114, v120
	v_cvt_pk_bf16_f32 v220, v100, v101
	v_cvt_pk_bf16_f32 v221, v102, v103
	v_cvt_pk_bf16_f32 v222, v104, v105
	v_cvt_pk_bf16_f32 v223, v106, v107
	v_cvt_pk_bf16_f32 v224, v108, v109
	v_cvt_pk_bf16_f32 v225, v110, v111
	s_waitcnt lgkmcnt(0)
	v_mfma_f32_32x32x16_bf16 v[20:35], v[116:119], v[198:201], v[20:35]
	v_mfma_f32_32x32x16_bf16 v[4:19], v[210:213], v[198:201], v[4:19]
	v_mfma_f32_32x32x16_bf16 v[20:35], v[206:209], v[202:205], v[20:35]
	ds_read_b128 v[198:201], v2 offset:18432
	ds_read_b128 v[206:209], v2 offset:19456
	ds_read_b128 v[210:213], v2 offset:22528
	ds_read_b128 v[226:229], v2 offset:23552
	v_mfma_f32_32x32x16_bf16 v[4:19], v[214:217], v[202:205], v[4:19]
	s_waitcnt lgkmcnt(0)
	v_mfma_f32_32x32x16_bf16 v[52:67], v[198:201], v[218:221], v[52:67]
	v_mfma_f32_32x32x16_bf16 v[36:51], v[210:213], v[218:221], v[36:51]
	v_mfma_f32_32x32x16_bf16 v[52:67], v[206:209], v[222:225], v[52:67]
	ds_read_b128 v[198:201], v2 offset:26624
	ds_read_b128 v[202:205], v2 offset:27648
	ds_read_b128 v[206:209], v2 offset:30720
	ds_read_b128 v[210:213], v2 offset:31744
	v_mfma_f32_32x32x16_bf16 v[36:51], v[226:229], v[222:225], v[36:51]
	s_waitcnt lgkmcnt(0)
	v_mfma_f32_32x32x16_bf16 v[20:35], v[198:201], v[218:221], v[20:35]
	v_mfma_f32_32x32x16_bf16 v[4:19], v[206:209], v[218:221], v[4:19]
	v_mfma_f32_32x32x16_bf16 v[20:35], v[202:205], v[222:225], v[20:35]
	v_mfma_f32_32x32x16_bf16 v[4:19], v[210:213], v[222:225], v[4:19]
	s_mov_b64 s[12:13], 0

; #define LAS __attribute__((address_space(3)))
; #define LAS __attribute__((address_space(3)))
; template <int MODE> __device__ __forceinline__ void attn_branch(const bf16* __restrict__ Kbase, const bf16* __restrict__ VTbase, int kt_lo, int kt_hi, int tq0, int t, int h, int q, int tid, int wave, ...
;     ...
;         if (need && (MODE == 1 || __ballot(sel) != 0ull)) {
;             const LAS unsigned char* fq = ldsl + buf * ATT_BUF + lane16;
;             const int mind = tq0 - (64 * kt + 63), maxd = tq0 + 31 - 64 * kt;
;             const float msk = sel ? 1.f : 0.f;
;             const int d0 = t - 64 * kt - 4 * h;
;             if (MODE == 0) {
;                 const int nearf = __builtin_amdgcn_readfirstlane(mind < 128 ? 1 : 0);
;                 attn_tile<MODE, 3>(fq, ldsl + tlane - 4 * d0, msk, nearf, qf, O, lsum);
;             } else if (mind >= 128) {
;                 if (maxd <= 511) attn_tile<MODE, 0>(fq, ldsl, msk, 0, qf, O, lsum);
;                 else attn_tile<MODE, 2>(fq, ldsl, msk, d0 - 512, qf, O, lsum);
;             } else attn_tile<MODE, 1>(fq, ldsl + tlane - 4 * d0, msk, 0, qf, O, lsum);
;         }
;         if (more) asm volatile("s_waitcnt vmcnt(4)" ::: "memory"); else asm volatile("s_waitcnt vmcnt(0)" ::: "memory");
.LBB0_1864:
	v_mov_b32_e32 v197, v184
	s_andn2_b64 vcc, exec, s[10:11]
	s_mov_b64 s[10:11], -1
	s_cbranch_vccz .LBB0_1867
